# non-temporal hint on the write-once f32 output stores (FFN2 layer 1) and on CONVERT's read-once f32 input loads
# baseline (speedup 1.0000x reference)
; DI int TID() { int t = (int)__builtin_amdgcn_workitem_id_x(); asm volatile("" : "+v"(t)); return t; }
; DI int BID() { int b = (int)__builtin_amdgcn_workgroup_id_x(); asm volatile("" : "+s"(b)); return b; }
; DI unsigned pk2(float a, float b) { f2_t v = {a, b}; bf2_t r = __builtin_convertvector(v, bf2_t); return __builtin_bit_cast(unsigned, r); }
; DI void phase_convert(const Params& p, const Chunk& ck) {
;   const float* xsrc = chunk_xsrc(p, 0, ck);
;   u16* xb = (u16*)(p.ws + OFF_XB); float* ps = (float*)(p.ws + OFF_PSIN);
;   const int tid = TID(), lane = tid & 63, w = tid >> 6;
;   for (int row = BID() * 4 + w; row < CT; row += gridDim.x * 4) {
;     float ss = 0.f;
; #pragma unroll
;     for (int i = 0; i < 2; ++i) {
;       const int c = (lane + 64 * i) * 8;
;       const f32x4 a = *(const f32x4*)(xsrc + (size_t)row * 1024 + c), b = *(const f32x4*)(xsrc + (size_t)row * 1024 + c + 4);
;       ss += a[0] * a[0] + a[1] * a[1] + a[2] * a[2] + a[3] * a[3] + b[0] * b[0] + b[1] * b[1] + b[2] * b[2] + b[3] * b[3];
;       *(u32x4*)(xb + (size_t)row * 1024 + c) = u32x4{pk2(a[0], a[1]), pk2(a[2], a[3]), pk2(b[0], b[1]), pk2(b[2], b[3])};
;     }
; #pragma unroll
;     for (int o = 32; o >= 1; o >>= 1) ss += __shfl_xor(ss, o);
;     if (lane < 16) ps[(size_t)row * 16 + lane] = (lane == 0) ? ss : 0.f;
;   }
.LBB1_194:
.LBB1_195:
	v_mov_b32_e32 v108, v2
	v_mov_b32_e32 v109, 0
	v_lshlrev_b64 v[16:17], 12, v[108:109]
	v_lshl_add_u64 v[16:17], v[6:7], 0, v[16:17]
	global_load_dwordx4 v[40:43], v[16:17], off nt
	global_load_dwordx4 v[44:47], v[16:17], off offset:16 nt
	global_load_dwordx4 v[48:51], v[16:17], off offset:2048 nt
	global_load_dwordx4 v[52:55], v[16:17], off offset:2064 nt
	v_add_u32_e32 v110, 0x800, v2
	v_mov_b32_e32 v111, 0
	v_lshlrev_b64 v[16:17], 12, v[110:111]
	v_lshl_add_u64 v[16:17], v[6:7], 0, v[16:17]
	global_load_dwordx4 v[56:59], v[16:17], off nt
	global_load_dwordx4 v[60:63], v[16:17], off offset:16 nt
	global_load_dwordx4 v[64:67], v[16:17], off offset:2048 nt
	global_load_dwordx4 v[68:71], v[16:17], off offset:2064 nt
	v_add_u32_e32 v112, 0x1000, v2
	v_mov_b32_e32 v113, 0
	v_lshlrev_b64 v[16:17], 12, v[112:113]
	v_lshl_add_u64 v[16:17], v[6:7], 0, v[16:17]
	global_load_dwordx4 v[72:75], v[16:17], off nt
	global_load_dwordx4 v[76:79], v[16:17], off offset:16 nt
	global_load_dwordx4 v[80:83], v[16:17], off offset:2048 nt
	global_load_dwordx4 v[84:87], v[16:17], off offset:2064 nt
	v_add_u32_e32 v114, 0x1800, v2
	v_mov_b32_e32 v115, 0
	v_lshlrev_b64 v[16:17], 12, v[114:115]
	v_lshl_add_u64 v[16:17], v[6:7], 0, v[16:17]
	global_load_dwordx4 v[88:91], v[16:17], off nt
	global_load_dwordx4 v[92:95], v[16:17], off offset:16 nt
	global_load_dwordx4 v[96:99], v[16:17], off offset:2048 nt
	global_load_dwordx4 v[100:103], v[16:17], off offset:2064 nt
	s_waitcnt vmcnt(12)
	v_mul_f32_e32 v104, v40, v40
	v_fmac_f32_e32 v104, v41, v41
	v_fmac_f32_e32 v104, v42, v42
	v_fmac_f32_e32 v104, v43, v43
	v_fmac_f32_e32 v104, v44, v44
	v_fmac_f32_e32 v104, v45, v45
	v_fmac_f32_e32 v104, v46, v46
	v_fmac_f32_e32 v104, v47, v47
	v_fmac_f32_e32 v104, v48, v48
	v_fmac_f32_e32 v104, v49, v49
	v_fmac_f32_e32 v104, v50, v50
	v_fmac_f32_e32 v104, v51, v51
	v_fmac_f32_e32 v104, v52, v52
	v_fmac_f32_e32 v104, v53, v53
	v_fmac_f32_e32 v104, v54, v54
	v_fmac_f32_e32 v104, v55, v55
	v_cvt_pk_bf16_f32 v40, v40, v41
	v_cvt_pk_bf16_f32 v41, v42, v43
	v_cvt_pk_bf16_f32 v42, v44, v45
	v_cvt_pk_bf16_f32 v43, v46, v47
	v_cvt_pk_bf16_f32 v44, v48, v49
	v_cvt_pk_bf16_f32 v45, v50, v51
	v_cvt_pk_bf16_f32 v46, v52, v53
	v_cvt_pk_bf16_f32 v47, v54, v55
	v_lshlrev_b64 v[16:17], 6, v[108:109]
	v_lshl_add_u64 v[16:17], v[8:9], 0, v[16:17]
	global_store_dwordx4 v[16:17], v[40:43], off
	v_lshl_add_u64 v[16:17], v[16:17], 0, s[16:17]
	global_store_dwordx4 v[16:17], v[44:47], off
	s_waitcnt vmcnt(8)
	v_mul_f32_e32 v105, v56, v56
	v_fmac_f32_e32 v105, v57, v57
	v_fmac_f32_e32 v105, v58, v58
	v_fmac_f32_e32 v105, v59, v59
	v_fmac_f32_e32 v105, v60, v60
	v_fmac_f32_e32 v105, v61, v61
	v_fmac_f32_e32 v105, v62, v62
	v_fmac_f32_e32 v105, v63, v63
	v_fmac_f32_e32 v105, v64, v64
	v_fmac_f32_e32 v105, v65, v65
	v_fmac_f32_e32 v105, v66, v66
	v_fmac_f32_e32 v105, v67, v67
	v_fmac_f32_e32 v105, v68, v68
	v_fmac_f32_e32 v105, v69, v69
	v_fmac_f32_e32 v105, v70, v70
	v_fmac_f32_e32 v105, v71, v71
	v_cvt_pk_bf16_f32 v56, v56, v57
	v_cvt_pk_bf16_f32 v57, v58, v59
	v_cvt_pk_bf16_f32 v58, v60, v61
	v_cvt_pk_bf16_f32 v59, v62, v63
	v_cvt_pk_bf16_f32 v60, v64, v65
	v_cvt_pk_bf16_f32 v61, v66, v67
	v_cvt_pk_bf16_f32 v62, v68, v69
	v_cvt_pk_bf16_f32 v63, v70, v71
	v_lshlrev_b64 v[16:17], 6, v[110:111]
	v_lshl_add_u64 v[16:17], v[8:9], 0, v[16:17]
	global_store_dwordx4 v[16:17], v[56:59], off
	v_lshl_add_u64 v[16:17], v[16:17], 0, s[16:17]
	global_store_dwordx4 v[16:17], v[60:63], off
	s_waitcnt vmcnt(4)
	v_mul_f32_e32 v106, v72, v72
	v_fmac_f32_e32 v106, v73, v73
	v_fmac_f32_e32 v106, v74, v74
	v_fmac_f32_e32 v106, v75, v75
	v_fmac_f32_e32 v106, v76, v76
	v_fmac_f32_e32 v106, v77, v77
	v_fmac_f32_e32 v106, v78, v78
	v_fmac_f32_e32 v106, v79, v79
	v_fmac_f32_e32 v106, v80, v80
	v_fmac_f32_e32 v106, v81, v81
	v_fmac_f32_e32 v106, v82, v82
	v_fmac_f32_e32 v106, v83, v83
	v_fmac_f32_e32 v106, v84, v84
	v_fmac_f32_e32 v106, v85, v85
	v_fmac_f32_e32 v106, v86, v86
	v_fmac_f32_e32 v106, v87, v87
	v_cvt_pk_bf16_f32 v72, v72, v73
	v_cvt_pk_bf16_f32 v73, v74, v75
	v_cvt_pk_bf16_f32 v74, v76, v77
	v_cvt_pk_bf16_f32 v75, v78, v79
	v_cvt_pk_bf16_f32 v76, v80, v81
	v_cvt_pk_bf16_f32 v77, v82, v83
	v_cvt_pk_bf16_f32 v78, v84, v85
	v_cvt_pk_bf16_f32 v79, v86, v87
	v_lshlrev_b64 v[16:17], 6, v[112:113]
	v_lshl_add_u64 v[16:17], v[8:9], 0, v[16:17]
	global_store_dwordx4 v[16:17], v[72:75], off
	v_lshl_add_u64 v[16:17], v[16:17], 0, s[16:17]
	global_store_dwordx4 v[16:17], v[76:79], off
	s_waitcnt vmcnt(0)
; DI unsigned pk2(float a, float b) { f2_t v = {a, b}; bf2_t r = __builtin_convertvector(v, bf2_t); return __builtin_bit_cast(unsigned, r); }
; DI void phase_convert(const Params& p, const Chunk& ck) {
;     ...
;       const f32x4 a = *(const f32x4*)(xsrc + (size_t)row * 1024 + c), b = *(const f32x4*)(xsrc + (size_t)row * 1024 + c + 4);
;       ss += a[0] * a[0] + a[1] * a[1] + a[2] * a[2] + a[3] * a[3] + b[0] * b[0] + b[1] * b[1] + b[2] * b[2] + b[3] * b[3];
;       *(u32x4*)(xb + (size_t)row * 1024 + c) = u32x4{pk2(a[0], a[1]), pk2(a[2], a[3]), pk2(b[0], b[1]), pk2(b[2], b[3])};
;     }
; #pragma unroll
;     for (int o = 32; o >= 1; o >>= 1) ss += __shfl_xor(ss, o);
;     if (lane < 16) ps[(size_t)row * 16 + lane] = (lane == 0) ? ss : 0.f;
;   }
	v_mul_f32_e32 v107, v88, v88
	v_fmac_f32_e32 v107, v89, v89
	v_fmac_f32_e32 v107, v90, v90
	v_fmac_f32_e32 v107, v91, v91
	v_fmac_f32_e32 v107, v92, v92
	v_fmac_f32_e32 v107, v93, v93
	v_fmac_f32_e32 v107, v94, v94
	v_fmac_f32_e32 v107, v95, v95
	v_fmac_f32_e32 v107, v96, v96
	v_fmac_f32_e32 v107, v97, v97
	v_fmac_f32_e32 v107, v98, v98
	v_fmac_f32_e32 v107, v99, v99
	v_fmac_f32_e32 v107, v100, v100
	v_fmac_f32_e32 v107, v101, v101
	v_fmac_f32_e32 v107, v102, v102
	v_fmac_f32_e32 v107, v103, v103
	v_cvt_pk_bf16_f32 v88, v88, v89
	v_cvt_pk_bf16_f32 v89, v90, v91
	v_cvt_pk_bf16_f32 v90, v92, v93
	v_cvt_pk_bf16_f32 v91, v94, v95
	v_cvt_pk_bf16_f32 v92, v96, v97
	v_cvt_pk_bf16_f32 v93, v98, v99
	v_cvt_pk_bf16_f32 v94, v100, v101
	v_cvt_pk_bf16_f32 v95, v102, v103
	v_lshlrev_b64 v[16:17], 6, v[114:115]
	v_lshl_add_u64 v[16:17], v[8:9], 0, v[16:17]
	global_store_dwordx4 v[16:17], v[88:91], off
	v_lshl_add_u64 v[16:17], v[16:17], 0, s[16:17]
	global_store_dwordx4 v[16:17], v[92:95], off
	v_add_f32_dpp v104, v104, v104 quad_perm:[1,0,3,2] row_mask:0xf bank_mask:0xf
	v_add_f32_dpp v105, v105, v105 quad_perm:[1,0,3,2] row_mask:0xf bank_mask:0xf
	v_add_f32_dpp v106, v106, v106 quad_perm:[1,0,3,2] row_mask:0xf bank_mask:0xf
	v_add_f32_dpp v107, v107, v107 quad_perm:[1,0,3,2] row_mask:0xf bank_mask:0xf
	v_add_f32_dpp v104, v104, v104 quad_perm:[2,3,0,1] row_mask:0xf bank_mask:0xf
	v_add_f32_dpp v105, v105, v105 quad_perm:[2,3,0,1] row_mask:0xf bank_mask:0xf
	v_add_f32_dpp v106, v106, v106 quad_perm:[2,3,0,1] row_mask:0xf bank_mask:0xf
	v_add_f32_dpp v107, v107, v107 quad_perm:[2,3,0,1] row_mask:0xf bank_mask:0xf
	v_add_f32_dpp v104, v104, v104 row_half_mirror row_mask:0xf bank_mask:0xf
	v_add_f32_dpp v105, v105, v105 row_half_mirror row_mask:0xf bank_mask:0xf
	v_add_f32_dpp v106, v106, v106 row_half_mirror row_mask:0xf bank_mask:0xf
	v_add_f32_dpp v107, v107, v107 row_half_mirror row_mask:0xf bank_mask:0xf
	v_add_f32_dpp v104, v104, v104 row_mirror row_mask:0xf bank_mask:0xf
	v_add_f32_dpp v105, v105, v105 row_mirror row_mask:0xf bank_mask:0xf
	v_add_f32_dpp v106, v106, v106 row_mirror row_mask:0xf bank_mask:0xf
	v_add_f32_dpp v107, v107, v107 row_mirror row_mask:0xf bank_mask:0xf
	ds_swizzle_b32 v116, v104 offset:0x401f
	ds_swizzle_b32 v117, v105 offset:0x401f
	ds_swizzle_b32 v118, v106 offset:0x401f
	ds_swizzle_b32 v119, v107 offset:0x401f
	s_waitcnt lgkmcnt(0)
	v_add_f32_e32 v104, v104, v116
	v_add_f32_e32 v105, v105, v117
	v_add_f32_e32 v106, v106, v118
	v_add_f32_e32 v107, v107, v119
	v_mov_b32_e32 v116, v104
	v_mov_b32_e32 v117, v105
	v_mov_b32_e32 v118, v106
	v_mov_b32_e32 v119, v107
	s_nop 1
	v_permlane32_swap_b32_e32 v104, v116
	v_permlane32_swap_b32_e32 v105, v117
	v_permlane32_swap_b32_e32 v106, v118
	v_permlane32_swap_b32_e32 v107, v119
	s_nop 1
	v_add_f32_e32 v104, v104, v116
	v_add_f32_e32 v105, v105, v117
	v_add_f32_e32 v106, v106, v118
	v_add_f32_e32 v107, v107, v119
	v_cndmask_b32_e64 v104, 0, v104, s[36:37]
	v_cndmask_b32_e64 v105, 0, v105, s[36:37]
	v_cndmask_b32_e64 v106, 0, v106, s[36:37]
	v_cndmask_b32_e64 v107, 0, v107, s[36:37]
	s_and_saveexec_b64 s[26:27], vcc
	v_lshlrev_b64 v[16:17], 6, v[108:109]
	v_lshl_add_u64 v[16:17], v[4:5], 0, v[16:17]
	global_store_dword v[16:17], v104, off
	v_lshlrev_b64 v[16:17], 6, v[110:111]
	v_lshl_add_u64 v[16:17], v[4:5], 0, v[16:17]
	global_store_dword v[16:17], v105, off
	v_lshlrev_b64 v[16:17], 6, v[112:113]
	v_lshl_add_u64 v[16:17], v[4:5], 0, v[16:17]
	global_store_dword v[16:17], v106, off
	v_lshlrev_b64 v[16:17], 6, v[114:115]
	v_lshl_add_u64 v[16:17], v[4:5], 0, v[16:17]
	global_store_dword v[16:17], v107, off
	s_or_b64 exec, exec, s[26:27]
	v_add_u32_e32 v108, 0x2000, v2
	v_mov_b32_e32 v109, 0
	v_lshlrev_b64 v[16:17], 12, v[108:109]
	v_lshl_add_u64 v[16:17], v[6:7], 0, v[16:17]
	global_load_dwordx4 v[40:43], v[16:17], off nt
	global_load_dwordx4 v[44:47], v[16:17], off offset:16 nt
	global_load_dwordx4 v[48:51], v[16:17], off offset:2048 nt
	global_load_dwordx4 v[52:55], v[16:17], off offset:2064 nt
	v_add_u32_e32 v110, 0x2800, v2
	v_mov_b32_e32 v111, 0
	v_lshlrev_b64 v[16:17], 12, v[110:111]
	v_lshl_add_u64 v[16:17], v[6:7], 0, v[16:17]
	global_load_dwordx4 v[56:59], v[16:17], off nt
	global_load_dwordx4 v[60:63], v[16:17], off offset:16 nt
	global_load_dwordx4 v[64:67], v[16:17], off offset:2048 nt
	global_load_dwordx4 v[68:71], v[16:17], off offset:2064 nt
	v_add_u32_e32 v112, 0x3000, v2
	v_mov_b32_e32 v113, 0
	v_lshlrev_b64 v[16:17], 12, v[112:113]
	v_lshl_add_u64 v[16:17], v[6:7], 0, v[16:17]
	global_load_dwordx4 v[72:75], v[16:17], off nt
	global_load_dwordx4 v[76:79], v[16:17], off offset:16 nt
	global_load_dwordx4 v[80:83], v[16:17], off offset:2048 nt
	global_load_dwordx4 v[84:87], v[16:17], off offset:2064 nt
	v_add_u32_e32 v114, 0x3800, v2
	v_mov_b32_e32 v115, 0
	v_lshlrev_b64 v[16:17], 12, v[114:115]
	v_lshl_add_u64 v[16:17], v[6:7], 0, v[16:17]
	global_load_dwordx4 v[88:91], v[16:17], off nt
	global_load_dwordx4 v[92:95], v[16:17], off offset:16 nt
	global_load_dwordx4 v[96:99], v[16:17], off offset:2048 nt
	global_load_dwordx4 v[100:103], v[16:17], off offset:2064 nt
	s_waitcnt vmcnt(12)
; DI unsigned pk2(float a, float b) { f2_t v = {a, b}; bf2_t r = __builtin_convertvector(v, bf2_t); return __builtin_bit_cast(unsigned, r); }
; DI void phase_convert(const Params& p, const Chunk& ck) {
;     ...
;     for (int i = 0; i < 2; ++i) {
;       const int c = (lane + 64 * i) * 8;
;       const f32x4 a = *(const f32x4*)(xsrc + (size_t)row * 1024 + c), b = *(const f32x4*)(xsrc + (size_t)row * 1024 + c + 4);
;       ss += a[0] * a[0] + a[1] * a[1] + a[2] * a[2] + a[3] * a[3] + b[0] * b[0] + b[1] * b[1] + b[2] * b[2] + b[3] * b[3];
;       *(u32x4*)(xb + (size_t)row * 1024 + c) = u32x4{pk2(a[0], a[1]), pk2(a[2], a[3]), pk2(b[0], b[1]), pk2(b[2], b[3])};
;     }
; #pragma unroll
;     for (int o = 32; o >= 1; o >>= 1) ss += __shfl_xor(ss, o);
;     if (lane < 16) ps[(size_t)row * 16 + lane] = (lane == 0) ? ss : 0.f;
	v_mul_f32_e32 v104, v40, v40
	v_fmac_f32_e32 v104, v41, v41
	v_fmac_f32_e32 v104, v42, v42
	v_fmac_f32_e32 v104, v43, v43
	v_fmac_f32_e32 v104, v44, v44
	v_fmac_f32_e32 v104, v45, v45
	v_fmac_f32_e32 v104, v46, v46
	v_fmac_f32_e32 v104, v47, v47
	v_fmac_f32_e32 v104, v48, v48
	v_fmac_f32_e32 v104, v49, v49
	v_fmac_f32_e32 v104, v50, v50
	v_fmac_f32_e32 v104, v51, v51
	v_fmac_f32_e32 v104, v52, v52
	v_fmac_f32_e32 v104, v53, v53
	v_fmac_f32_e32 v104, v54, v54
	v_fmac_f32_e32 v104, v55, v55
	v_cvt_pk_bf16_f32 v40, v40, v41
	v_cvt_pk_bf16_f32 v41, v42, v43
	v_cvt_pk_bf16_f32 v42, v44, v45
	v_cvt_pk_bf16_f32 v43, v46, v47
	v_cvt_pk_bf16_f32 v44, v48, v49
	v_cvt_pk_bf16_f32 v45, v50, v51
	v_cvt_pk_bf16_f32 v46, v52, v53
	v_cvt_pk_bf16_f32 v47, v54, v55
	v_lshlrev_b64 v[16:17], 6, v[108:109]
	v_lshl_add_u64 v[16:17], v[8:9], 0, v[16:17]
	global_store_dwordx4 v[16:17], v[40:43], off
	v_lshl_add_u64 v[16:17], v[16:17], 0, s[16:17]
	global_store_dwordx4 v[16:17], v[44:47], off
	s_waitcnt vmcnt(8)
	v_mul_f32_e32 v105, v56, v56
	v_fmac_f32_e32 v105, v57, v57
	v_fmac_f32_e32 v105, v58, v58
	v_fmac_f32_e32 v105, v59, v59
	v_fmac_f32_e32 v105, v60, v60
	v_fmac_f32_e32 v105, v61, v61
	v_fmac_f32_e32 v105, v62, v62
	v_fmac_f32_e32 v105, v63, v63
	v_fmac_f32_e32 v105, v64, v64
	v_fmac_f32_e32 v105, v65, v65
	v_fmac_f32_e32 v105, v66, v66
	v_fmac_f32_e32 v105, v67, v67
	v_fmac_f32_e32 v105, v68, v68
	v_fmac_f32_e32 v105, v69, v69
	v_fmac_f32_e32 v105, v70, v70
	v_fmac_f32_e32 v105, v71, v71
	v_cvt_pk_bf16_f32 v56, v56, v57
	v_cvt_pk_bf16_f32 v57, v58, v59
	v_cvt_pk_bf16_f32 v58, v60, v61
	v_cvt_pk_bf16_f32 v59, v62, v63
	v_cvt_pk_bf16_f32 v60, v64, v65
	v_cvt_pk_bf16_f32 v61, v66, v67
	v_cvt_pk_bf16_f32 v62, v68, v69
	v_cvt_pk_bf16_f32 v63, v70, v71
	v_lshlrev_b64 v[16:17], 6, v[110:111]
	v_lshl_add_u64 v[16:17], v[8:9], 0, v[16:17]
	global_store_dwordx4 v[16:17], v[56:59], off
	v_lshl_add_u64 v[16:17], v[16:17], 0, s[16:17]
	global_store_dwordx4 v[16:17], v[60:63], off
	s_waitcnt vmcnt(4)
	v_mul_f32_e32 v106, v72, v72
	v_fmac_f32_e32 v106, v73, v73
	v_fmac_f32_e32 v106, v74, v74
	v_fmac_f32_e32 v106, v75, v75
	v_fmac_f32_e32 v106, v76, v76
	v_fmac_f32_e32 v106, v77, v77
	v_fmac_f32_e32 v106, v78, v78
	v_fmac_f32_e32 v106, v79, v79
	v_fmac_f32_e32 v106, v80, v80
	v_fmac_f32_e32 v106, v81, v81
	v_fmac_f32_e32 v106, v82, v82
	v_fmac_f32_e32 v106, v83, v83
	v_fmac_f32_e32 v106, v84, v84
	v_fmac_f32_e32 v106, v85, v85
	v_fmac_f32_e32 v106, v86, v86
	v_fmac_f32_e32 v106, v87, v87
	v_cvt_pk_bf16_f32 v72, v72, v73
	v_cvt_pk_bf16_f32 v73, v74, v75
	v_cvt_pk_bf16_f32 v74, v76, v77
	v_cvt_pk_bf16_f32 v75, v78, v79
	v_cvt_pk_bf16_f32 v76, v80, v81
	v_cvt_pk_bf16_f32 v77, v82, v83
	v_cvt_pk_bf16_f32 v78, v84, v85
	v_cvt_pk_bf16_f32 v79, v86, v87
	v_lshlrev_b64 v[16:17], 6, v[112:113]
	v_lshl_add_u64 v[16:17], v[8:9], 0, v[16:17]
	global_store_dwordx4 v[16:17], v[72:75], off
	v_lshl_add_u64 v[16:17], v[16:17], 0, s[16:17]
	global_store_dwordx4 v[16:17], v[76:79], off
	s_waitcnt vmcnt(0)
	v_mul_f32_e32 v107, v88, v88
	v_fmac_f32_e32 v107, v89, v89
	v_fmac_f32_e32 v107, v90, v90
	v_fmac_f32_e32 v107, v91, v91
	v_fmac_f32_e32 v107, v92, v92
	v_fmac_f32_e32 v107, v93, v93
	v_fmac_f32_e32 v107, v94, v94
	v_fmac_f32_e32 v107, v95, v95
	v_fmac_f32_e32 v107, v96, v96
	v_fmac_f32_e32 v107, v97, v97
	v_fmac_f32_e32 v107, v98, v98
	v_fmac_f32_e32 v107, v99, v99
	v_fmac_f32_e32 v107, v100, v100
	v_fmac_f32_e32 v107, v101, v101
	v_fmac_f32_e32 v107, v102, v102
	v_fmac_f32_e32 v107, v103, v103
	v_cvt_pk_bf16_f32 v88, v88, v89
	v_cvt_pk_bf16_f32 v89, v90, v91
	v_cvt_pk_bf16_f32 v90, v92, v93
	v_cvt_pk_bf16_f32 v91, v94, v95
	v_cvt_pk_bf16_f32 v92, v96, v97
	v_cvt_pk_bf16_f32 v93, v98, v99
	v_cvt_pk_bf16_f32 v94, v100, v101
	v_cvt_pk_bf16_f32 v95, v102, v103
	v_lshlrev_b64 v[16:17], 6, v[114:115]
	v_lshl_add_u64 v[16:17], v[8:9], 0, v[16:17]
	global_store_dwordx4 v[16:17], v[88:91], off
	v_lshl_add_u64 v[16:17], v[16:17], 0, s[16:17]
	global_store_dwordx4 v[16:17], v[92:95], off
	v_add_f32_dpp v104, v104, v104 quad_perm:[1,0,3,2] row_mask:0xf bank_mask:0xf
	v_add_f32_dpp v105, v105, v105 quad_perm:[1,0,3,2] row_mask:0xf bank_mask:0xf
	v_add_f32_dpp v106, v106, v106 quad_perm:[1,0,3,2] row_mask:0xf bank_mask:0xf
	v_add_f32_dpp v107, v107, v107 quad_perm:[1,0,3,2] row_mask:0xf bank_mask:0xf
	v_add_f32_dpp v104, v104, v104 quad_perm:[2,3,0,1] row_mask:0xf bank_mask:0xf
	v_add_f32_dpp v105, v105, v105 quad_perm:[2,3,0,1] row_mask:0xf bank_mask:0xf
	v_add_f32_dpp v106, v106, v106 quad_perm:[2,3,0,1] row_mask:0xf bank_mask:0xf
	v_add_f32_dpp v107, v107, v107 quad_perm:[2,3,0,1] row_mask:0xf bank_mask:0xf
	v_add_f32_dpp v104, v104, v104 row_half_mirror row_mask:0xf bank_mask:0xf
	v_add_f32_dpp v105, v105, v105 row_half_mirror row_mask:0xf bank_mask:0xf
	v_add_f32_dpp v106, v106, v106 row_half_mirror row_mask:0xf bank_mask:0xf
	v_add_f32_dpp v107, v107, v107 row_half_mirror row_mask:0xf bank_mask:0xf
	v_add_f32_dpp v104, v104, v104 row_mirror row_mask:0xf bank_mask:0xf
	v_add_f32_dpp v105, v105, v105 row_mirror row_mask:0xf bank_mask:0xf
	v_add_f32_dpp v106, v106, v106 row_mirror row_mask:0xf bank_mask:0xf
	v_add_f32_dpp v107, v107, v107 row_mirror row_mask:0xf bank_mask:0xf
	ds_swizzle_b32 v116, v104 offset:0x401f
	ds_swizzle_b32 v117, v105 offset:0x401f
	ds_swizzle_b32 v118, v106 offset:0x401f
	ds_swizzle_b32 v119, v107 offset:0x401f
	s_waitcnt lgkmcnt(0)
	v_add_f32_e32 v104, v104, v116
	v_add_f32_e32 v105, v105, v117
	v_add_f32_e32 v106, v106, v118
	v_add_f32_e32 v107, v107, v119
	v_mov_b32_e32 v116, v104
	v_mov_b32_e32 v117, v105
	v_mov_b32_e32 v118, v106
	v_mov_b32_e32 v119, v107
	s_nop 1
	v_permlane32_swap_b32_e32 v104, v116
	v_permlane32_swap_b32_e32 v105, v117
	v_permlane32_swap_b32_e32 v106, v118
	v_permlane32_swap_b32_e32 v107, v119
	s_nop 1
	v_add_f32_e32 v104, v104, v116
	v_add_f32_e32 v105, v105, v117
	v_add_f32_e32 v106, v106, v118
	v_add_f32_e32 v107, v107, v119
	v_cndmask_b32_e64 v104, 0, v104, s[36:37]
	v_cndmask_b32_e64 v105, 0, v105, s[36:37]
	v_cndmask_b32_e64 v106, 0, v106, s[36:37]
	v_cndmask_b32_e64 v107, 0, v107, s[36:37]
	s_and_saveexec_b64 s[26:27], vcc
	v_lshlrev_b64 v[16:17], 6, v[108:109]
	v_lshl_add_u64 v[16:17], v[4:5], 0, v[16:17]
	global_store_dword v[16:17], v104, off
	v_lshlrev_b64 v[16:17], 6, v[110:111]
	v_lshl_add_u64 v[16:17], v[4:5], 0, v[16:17]
	global_store_dword v[16:17], v105, off
	v_lshlrev_b64 v[16:17], 6, v[112:113]
	v_lshl_add_u64 v[16:17], v[4:5], 0, v[16:17]
	global_store_dword v[16:17], v106, off
	v_lshlrev_b64 v[16:17], 6, v[114:115]
	v_lshl_add_u64 v[16:17], v[4:5], 0, v[16:17]
	global_store_dword v[16:17], v107, off
	s_or_b64 exec, exec, s[26:27]

; DI u32x4 pack8(const float (&v)[8]) { u32x4 r = {pk2(v[0], v[1]), pk2(v[2], v[3]), pk2(v[4], v[5]), pk2(v[6], v[7])}; return r; }
; DI void tile_ffn2(const Params& p, int l, const Chunk& ck, int tile, int next, PF& pf, char* smem) {
;     ...
;   const int row = tid >> 1, half = tid & 1; float ssq = 0.f;
;   float* xd = p.out + (size_t)(ck.tok0 + m0 + row) * 1024 + n0 + half * 64;
;   u16* xb = (u16*)(p.ws + OFF_XB) + (size_t)(m0 + row) * 1024 + n0 + half * 64;
; #pragma unroll
;   for (int c8 = 0; c8 < 8; ++c8) {
;     float v[8], x[8]; cs_ld8(Cs, row, half * 64 + c8 * 8, v); unpack8(*(const u32x4*)(xb + c8 * 8), x);
; #pragma unroll
;     for (int j = 0; j < 8; ++j) { v[j] += x[j]; ssq += v[j] * v[j]; }
;     if (l == 0) *(u32x4*)(xb + c8 * 8) = pack8(v);
;     else { *(f32x4*)(xd + c8 * 8) = f32x4{v[0], v[1], v[2], v[3]}; *(f32x4*)(xd + c8 * 8 + 4) = f32x4{v[4], v[5], v[6], v[7]}; }
;   }
.Lffn2_l1:
	global_load_dwordx2 v[224:225], v164, s[50:51] offset:0
	global_load_dwordx2 v[226:227], v164, s[50:51] offset:32
	global_load_dwordx2 v[228:229], v122, s[50:51] offset:0
	global_load_dwordx2 v[230:231], v122, s[50:51] offset:32
	global_load_dwordx2 v[232:233], v164, s[50:51] offset:1024
	global_load_dwordx2 v[234:235], v164, s[50:51] offset:1056
	global_load_dwordx2 v[236:237], v122, s[50:51] offset:1024
	global_load_dwordx2 v[238:239], v122, s[50:51] offset:1056
	global_load_dwordx2 v[240:241], v164, s[50:51] offset:2048
	global_load_dwordx2 v[242:243], v164, s[50:51] offset:2080
	global_load_dwordx2 v[244:245], v122, s[50:51] offset:2048
	global_load_dwordx2 v[246:247], v122, s[50:51] offset:2080
	global_load_dwordx2 v[248:249], v164, s[50:51] offset:3072
	global_load_dwordx2 v[250:251], v164, s[50:51] offset:3104
	global_load_dwordx2 v[156:157], v122, s[50:51] offset:3072
	global_load_dwordx2 v[158:159], v122, s[50:51] offset:3104
	s_waitcnt vmcnt(0)
	v_lshlrev_b32_e32 v167, 16, v224
	v_and_b32_e32 v168, 0xffff0000, v224
	v_lshlrev_b32_e32 v169, 16, v225
	v_and_b32_e32 v170, 0xffff0000, v225
	v_add_f32_e32 v2, v2, v167
	v_add_f32_e32 v3, v3, v168
	v_add_f32_e32 v4, v4, v169
	v_add_f32_e32 v5, v5, v170
	global_store_dwordx4 v165, v[2:5], s[12:13] nt
	v_lshlrev_b32_e32 v167, 16, v226
	v_and_b32_e32 v168, 0xffff0000, v226
	v_lshlrev_b32_e32 v169, 16, v227
	v_and_b32_e32 v170, 0xffff0000, v227
	v_add_f32_e32 v6, v6, v167
	v_add_f32_e32 v7, v7, v168
	v_add_f32_e32 v8, v8, v169
	v_add_f32_e32 v9, v9, v170
	global_store_dwordx4 v165, v[6:9], s[12:13] offset:64 nt
	v_lshlrev_b32_e32 v167, 16, v228
	v_and_b32_e32 v168, 0xffff0000, v228
	v_lshlrev_b32_e32 v169, 16, v229
	v_and_b32_e32 v170, 0xffff0000, v229
	v_add_f32_e32 v10, v10, v167
	v_add_f32_e32 v11, v11, v168
	v_add_f32_e32 v12, v12, v169
	v_add_f32_e32 v13, v13, v170
	global_store_dwordx4 v165, v[10:13], s[12:13] offset:128 nt
	v_lshlrev_b32_e32 v167, 16, v230
	v_and_b32_e32 v168, 0xffff0000, v230
	v_lshlrev_b32_e32 v169, 16, v231
	v_and_b32_e32 v170, 0xffff0000, v231
	v_add_f32_e32 v14, v14, v167
	v_add_f32_e32 v15, v15, v168
	v_add_f32_e32 v16, v16, v169
	v_add_f32_e32 v17, v17, v170
	global_store_dwordx4 v165, v[14:17], s[12:13] offset:192 nt
	v_add_u32_e32 v165, 0x10000, v165
	v_lshlrev_b32_e32 v167, 16, v232
	v_and_b32_e32 v168, 0xffff0000, v232
	v_lshlrev_b32_e32 v169, 16, v233
	v_and_b32_e32 v170, 0xffff0000, v233
	v_add_f32_e32 v18, v18, v167
	v_add_f32_e32 v19, v19, v168
	v_add_f32_e32 v20, v20, v169
	v_add_f32_e32 v21, v21, v170
	global_store_dwordx4 v165, v[18:21], s[12:13] nt
	v_lshlrev_b32_e32 v167, 16, v234
	v_and_b32_e32 v168, 0xffff0000, v234
	v_lshlrev_b32_e32 v169, 16, v235
	v_and_b32_e32 v170, 0xffff0000, v235
	v_add_f32_e32 v22, v22, v167
	v_add_f32_e32 v23, v23, v168
	v_add_f32_e32 v24, v24, v169
	v_add_f32_e32 v25, v25, v170
	global_store_dwordx4 v165, v[22:25], s[12:13] offset:64 nt
	v_lshlrev_b32_e32 v167, 16, v236
	v_and_b32_e32 v168, 0xffff0000, v236
	v_lshlrev_b32_e32 v169, 16, v237
	v_and_b32_e32 v170, 0xffff0000, v237
	v_add_f32_e32 v26, v26, v167
	v_add_f32_e32 v27, v27, v168
	v_add_f32_e32 v28, v28, v169
	v_add_f32_e32 v29, v29, v170
	global_store_dwordx4 v165, v[26:29], s[12:13] offset:128 nt
	v_lshlrev_b32_e32 v167, 16, v238
	v_and_b32_e32 v168, 0xffff0000, v238
	v_lshlrev_b32_e32 v169, 16, v239
	v_and_b32_e32 v170, 0xffff0000, v239
	v_add_f32_e32 v30, v30, v167
	v_add_f32_e32 v31, v31, v168
	v_add_f32_e32 v32, v32, v169
	v_add_f32_e32 v33, v33, v170
	global_store_dwordx4 v165, v[30:33], s[12:13] offset:192 nt
	v_add_u32_e32 v165, 0x10000, v165
	v_lshlrev_b32_e32 v167, 16, v240
	v_and_b32_e32 v168, 0xffff0000, v240
	v_lshlrev_b32_e32 v169, 16, v241
	v_and_b32_e32 v170, 0xffff0000, v241
	v_add_f32_e32 v34, v34, v167
	v_add_f32_e32 v35, v35, v168
	v_add_f32_e32 v36, v36, v169
	v_add_f32_e32 v37, v37, v170
	global_store_dwordx4 v165, v[34:37], s[12:13] nt
	v_lshlrev_b32_e32 v167, 16, v242
	v_and_b32_e32 v168, 0xffff0000, v242
	v_lshlrev_b32_e32 v169, 16, v243
	v_and_b32_e32 v170, 0xffff0000, v243
	v_add_f32_e32 v38, v38, v167
	v_add_f32_e32 v39, v39, v168
	v_add_f32_e32 v40, v40, v169
	v_add_f32_e32 v41, v41, v170
	global_store_dwordx4 v165, v[38:41], s[12:13] offset:64 nt
	v_lshlrev_b32_e32 v167, 16, v244
	v_and_b32_e32 v168, 0xffff0000, v244
	v_lshlrev_b32_e32 v169, 16, v245
	v_and_b32_e32 v170, 0xffff0000, v245
	v_add_f32_e32 v42, v42, v167
	v_add_f32_e32 v43, v43, v168
	v_add_f32_e32 v44, v44, v169
	v_add_f32_e32 v45, v45, v170
	global_store_dwordx4 v165, v[42:45], s[12:13] offset:128 nt
	v_lshlrev_b32_e32 v167, 16, v246
	v_and_b32_e32 v168, 0xffff0000, v246
	v_lshlrev_b32_e32 v169, 16, v247
	v_and_b32_e32 v170, 0xffff0000, v247
	v_add_f32_e32 v46, v46, v167
	v_add_f32_e32 v47, v47, v168
	v_add_f32_e32 v48, v48, v169
	v_add_f32_e32 v49, v49, v170
	global_store_dwordx4 v165, v[46:49], s[12:13] offset:192 nt
	v_add_u32_e32 v165, 0x10000, v165
	v_lshlrev_b32_e32 v167, 16, v248
	v_and_b32_e32 v168, 0xffff0000, v248
	v_lshlrev_b32_e32 v169, 16, v249
	v_and_b32_e32 v170, 0xffff0000, v249
	v_add_f32_e32 v50, v50, v167
	v_add_f32_e32 v51, v51, v168
	v_add_f32_e32 v52, v52, v169
	v_add_f32_e32 v53, v53, v170
	global_store_dwordx4 v165, v[50:53], s[12:13] nt
	v_lshlrev_b32_e32 v167, 16, v250
	v_and_b32_e32 v168, 0xffff0000, v250
	v_lshlrev_b32_e32 v169, 16, v251
	v_and_b32_e32 v170, 0xffff0000, v251
	v_add_f32_e32 v54, v54, v167
	v_add_f32_e32 v55, v55, v168
	v_add_f32_e32 v56, v56, v169
	v_add_f32_e32 v57, v57, v170
	global_store_dwordx4 v165, v[54:57], s[12:13] offset:64 nt
	v_lshlrev_b32_e32 v167, 16, v156
	v_and_b32_e32 v168, 0xffff0000, v156
; DI u32x4 pack8(const float (&v)[8]) { u32x4 r = {pk2(v[0], v[1]), pk2(v[2], v[3]), pk2(v[4], v[5]), pk2(v[6], v[7])}; return r; }
; DI void tile_ffn2(const Params& p, int l, const Chunk& ck, int tile, int next, PF& pf, char* smem) {
;     ...
; #pragma unroll
;   for (int c8 = 0; c8 < 8; ++c8) {
;     float v[8], x[8]; cs_ld8(Cs, row, half * 64 + c8 * 8, v); unpack8(*(const u32x4*)(xb + c8 * 8), x);
; #pragma unroll
;     for (int j = 0; j < 8; ++j) { v[j] += x[j]; ssq += v[j] * v[j]; }
;     if (l == 0) *(u32x4*)(xb + c8 * 8) = pack8(v);
;     else { *(f32x4*)(xd + c8 * 8) = f32x4{v[0], v[1], v[2], v[3]}; *(f32x4*)(xd + c8 * 8 + 4) = f32x4{v[4], v[5], v[6], v[7]}; }
;   }
	v_lshlrev_b32_e32 v169, 16, v157
	v_and_b32_e32 v170, 0xffff0000, v157
	v_add_f32_e32 v58, v58, v167
	v_add_f32_e32 v59, v59, v168
	v_add_f32_e32 v60, v60, v169
	v_add_f32_e32 v61, v61, v170
	global_store_dwordx4 v165, v[58:61], s[12:13] offset:128 nt
	v_lshlrev_b32_e32 v167, 16, v158
	v_and_b32_e32 v168, 0xffff0000, v158
	v_lshlrev_b32_e32 v169, 16, v159
	v_and_b32_e32 v170, 0xffff0000, v159
	v_add_f32_e32 v62, v62, v167
	v_add_f32_e32 v63, v63, v168
	v_add_f32_e32 v64, v64, v169
	v_add_f32_e32 v65, v65, v170
	global_store_dwordx4 v165, v[62:65], s[12:13] offset:192 nt
	v_subrev_u32_e32 v165, 0x30000, v165
	v_add_u32_e32 v164, 0x400000, v164
	v_add_u32_e32 v122, 0x400000, v122
	global_load_dwordx2 v[224:225], v164, s[50:51] offset:0
	global_load_dwordx2 v[226:227], v164, s[50:51] offset:32
	global_load_dwordx2 v[228:229], v122, s[50:51] offset:0
	global_load_dwordx2 v[230:231], v122, s[50:51] offset:32
	global_load_dwordx2 v[232:233], v164, s[50:51] offset:1024
	global_load_dwordx2 v[234:235], v164, s[50:51] offset:1056
	global_load_dwordx2 v[236:237], v122, s[50:51] offset:1024
	global_load_dwordx2 v[238:239], v122, s[50:51] offset:1056
	global_load_dwordx2 v[240:241], v164, s[50:51] offset:2048
	global_load_dwordx2 v[242:243], v164, s[50:51] offset:2080
	global_load_dwordx2 v[244:245], v122, s[50:51] offset:2048
	global_load_dwordx2 v[246:247], v122, s[50:51] offset:2080
	global_load_dwordx2 v[248:249], v164, s[50:51] offset:3072
	global_load_dwordx2 v[250:251], v164, s[50:51] offset:3104
	global_load_dwordx2 v[156:157], v122, s[50:51] offset:3072
	global_load_dwordx2 v[158:159], v122, s[50:51] offset:3104
	s_waitcnt vmcnt(0)
; DI u32x4 pack8(const float (&v)[8]) { u32x4 r = {pk2(v[0], v[1]), pk2(v[2], v[3]), pk2(v[4], v[5]), pk2(v[6], v[7])}; return r; }
; DI void tile_ffn2(const Params& p, int l, const Chunk& ck, int tile, int next, PF& pf, char* smem) {
;     ...
; #pragma unroll
;   for (int c8 = 0; c8 < 8; ++c8) {
;     float v[8], x[8]; cs_ld8(Cs, row, half * 64 + c8 * 8, v); unpack8(*(const u32x4*)(xb + c8 * 8), x);
; #pragma unroll
;     for (int j = 0; j < 8; ++j) { v[j] += x[j]; ssq += v[j] * v[j]; }
;     if (l == 0) *(u32x4*)(xb + c8 * 8) = pack8(v);
;     else { *(f32x4*)(xd + c8 * 8) = f32x4{v[0], v[1], v[2], v[3]}; *(f32x4*)(xd + c8 * 8 + 4) = f32x4{v[4], v[5], v[6], v[7]}; }
;   }
	v_lshlrev_b32_e32 v167, 16, v224
	v_and_b32_e32 v168, 0xffff0000, v224
	v_lshlrev_b32_e32 v169, 16, v225
	v_and_b32_e32 v170, 0xffff0000, v225
	v_add_f32_e32 v74, v74, v167
	v_add_f32_e32 v75, v75, v168
	v_add_f32_e32 v76, v76, v169
	v_add_f32_e32 v77, v77, v170
	global_store_dwordx4 v165, v[74:77], s[12:13] offset:512 nt
	v_lshlrev_b32_e32 v167, 16, v226
	v_and_b32_e32 v168, 0xffff0000, v226
	v_lshlrev_b32_e32 v169, 16, v227
	v_and_b32_e32 v170, 0xffff0000, v227
	v_add_f32_e32 v78, v78, v167
	v_add_f32_e32 v79, v79, v168
	v_add_f32_e32 v80, v80, v169
	v_add_f32_e32 v81, v81, v170
	global_store_dwordx4 v165, v[78:81], s[12:13] offset:576 nt
	v_lshlrev_b32_e32 v167, 16, v228
	v_and_b32_e32 v168, 0xffff0000, v228
	v_lshlrev_b32_e32 v169, 16, v229
	v_and_b32_e32 v170, 0xffff0000, v229
	v_add_f32_e32 v82, v82, v167
	v_add_f32_e32 v83, v83, v168
	v_add_f32_e32 v84, v84, v169
	v_add_f32_e32 v85, v85, v170
	global_store_dwordx4 v165, v[82:85], s[12:13] offset:640 nt
	v_lshlrev_b32_e32 v167, 16, v230
	v_and_b32_e32 v168, 0xffff0000, v230
	v_lshlrev_b32_e32 v169, 16, v231
	v_and_b32_e32 v170, 0xffff0000, v231
	v_add_f32_e32 v86, v86, v167
	v_add_f32_e32 v87, v87, v168
	v_add_f32_e32 v88, v88, v169
	v_add_f32_e32 v89, v89, v170
	global_store_dwordx4 v165, v[86:89], s[12:13] offset:704 nt
	v_add_u32_e32 v165, 0x10000, v165
	v_lshlrev_b32_e32 v167, 16, v232
	v_and_b32_e32 v168, 0xffff0000, v232
	v_lshlrev_b32_e32 v169, 16, v233
	v_and_b32_e32 v170, 0xffff0000, v233
	v_add_f32_e32 v90, v90, v167
	v_add_f32_e32 v91, v91, v168
	v_add_f32_e32 v92, v92, v169
	v_add_f32_e32 v93, v93, v170
	global_store_dwordx4 v165, v[90:93], s[12:13] offset:512 nt
	v_lshlrev_b32_e32 v167, 16, v234
	v_and_b32_e32 v168, 0xffff0000, v234
	v_lshlrev_b32_e32 v169, 16, v235
	v_and_b32_e32 v170, 0xffff0000, v235
	v_add_f32_e32 v94, v94, v167
	v_add_f32_e32 v95, v95, v168
	v_add_f32_e32 v96, v96, v169
	v_add_f32_e32 v97, v97, v170
	global_store_dwordx4 v165, v[94:97], s[12:13] offset:576 nt
	v_lshlrev_b32_e32 v167, 16, v236
	v_and_b32_e32 v168, 0xffff0000, v236
	v_lshlrev_b32_e32 v169, 16, v237
	v_and_b32_e32 v170, 0xffff0000, v237
	v_add_f32_e32 v98, v98, v167
	v_add_f32_e32 v99, v99, v168
	v_add_f32_e32 v100, v100, v169
	v_add_f32_e32 v101, v101, v170
	global_store_dwordx4 v165, v[98:101], s[12:13] offset:640 nt
	v_lshlrev_b32_e32 v167, 16, v238
	v_and_b32_e32 v168, 0xffff0000, v238
	v_lshlrev_b32_e32 v169, 16, v239
	v_and_b32_e32 v170, 0xffff0000, v239
	v_add_f32_e32 v102, v102, v167
	v_add_f32_e32 v103, v103, v168
	v_add_f32_e32 v104, v104, v169
	v_add_f32_e32 v105, v105, v170
	global_store_dwordx4 v165, v[102:105], s[12:13] offset:704 nt
	v_add_u32_e32 v165, 0x10000, v165
	v_lshlrev_b32_e32 v167, 16, v240
	v_and_b32_e32 v168, 0xffff0000, v240
	v_lshlrev_b32_e32 v169, 16, v241
	v_and_b32_e32 v170, 0xffff0000, v241
	v_add_f32_e32 v106, v106, v167
	v_add_f32_e32 v107, v107, v168
	v_add_f32_e32 v108, v108, v169
	v_add_f32_e32 v109, v109, v170
	global_store_dwordx4 v165, v[106:109], s[12:13] offset:512 nt
	v_lshlrev_b32_e32 v167, 16, v242
	v_and_b32_e32 v168, 0xffff0000, v242
	v_lshlrev_b32_e32 v169, 16, v243
	v_and_b32_e32 v170, 0xffff0000, v243
	v_add_f32_e32 v110, v110, v167
	v_add_f32_e32 v111, v111, v168
	v_add_f32_e32 v112, v112, v169
	v_add_f32_e32 v113, v113, v170
	global_store_dwordx4 v165, v[110:113], s[12:13] offset:576 nt
	v_lshlrev_b32_e32 v167, 16, v244
	v_and_b32_e32 v168, 0xffff0000, v244
	v_lshlrev_b32_e32 v169, 16, v245
	v_and_b32_e32 v170, 0xffff0000, v245
	v_add_f32_e32 v114, v114, v167
	v_add_f32_e32 v115, v115, v168
	v_add_f32_e32 v116, v116, v169
	v_add_f32_e32 v117, v117, v170
	global_store_dwordx4 v165, v[114:117], s[12:13] offset:640 nt
	v_lshlrev_b32_e32 v167, 16, v246
	v_and_b32_e32 v168, 0xffff0000, v246
	v_lshlrev_b32_e32 v169, 16, v247
	v_and_b32_e32 v170, 0xffff0000, v247
	v_add_f32_e32 v118, v118, v167
	v_add_f32_e32 v119, v119, v168
	v_add_f32_e32 v120, v120, v169
	v_add_f32_e32 v121, v121, v170
	global_store_dwordx4 v165, v[118:121], s[12:13] offset:704 nt
	v_add_u32_e32 v165, 0x10000, v165
	v_lshlrev_b32_e32 v167, 16, v248
	v_and_b32_e32 v168, 0xffff0000, v248
	v_lshlrev_b32_e32 v169, 16, v249
	v_and_b32_e32 v170, 0xffff0000, v249
	v_add_f32_e32 v208, v208, v167
	v_add_f32_e32 v209, v209, v168
	v_add_f32_e32 v210, v210, v169
	v_add_f32_e32 v211, v211, v170
	global_store_dwordx4 v165, v[208:211], s[12:13] offset:512 nt
	v_lshlrev_b32_e32 v167, 16, v250
	v_and_b32_e32 v168, 0xffff0000, v250
	v_lshlrev_b32_e32 v169, 16, v251
	v_and_b32_e32 v170, 0xffff0000, v251
	v_add_f32_e32 v212, v212, v167
	v_add_f32_e32 v213, v213, v168
	v_add_f32_e32 v214, v214, v169
	v_add_f32_e32 v215, v215, v170
	global_store_dwordx4 v165, v[212:215], s[12:13] offset:576 nt
	v_lshlrev_b32_e32 v167, 16, v156
	v_and_b32_e32 v168, 0xffff0000, v156
	v_lshlrev_b32_e32 v169, 16, v157
	v_and_b32_e32 v170, 0xffff0000, v157
	v_add_f32_e32 v216, v216, v167
	v_add_f32_e32 v217, v217, v168
	v_add_f32_e32 v218, v218, v169
	v_add_f32_e32 v219, v219, v170
	global_store_dwordx4 v165, v[216:219], s[12:13] offset:640 nt
	v_lshlrev_b32_e32 v167, 16, v158
	v_and_b32_e32 v168, 0xffff0000, v158
	v_lshlrev_b32_e32 v169, 16, v159
	v_and_b32_e32 v170, 0xffff0000, v159
	v_add_f32_e32 v220, v220, v167
	v_add_f32_e32 v221, v221, v168
	v_add_f32_e32 v222, v222, v169
	v_add_f32_e32 v223, v223, v170
	global_store_dwordx4 v165, v[220:223], s[12:13] offset:704 nt
	v_subrev_u32_e32 v165, 0x30000, v165
